# sample-scan / sample-attention queues: item-index atomic issued one item ahead (fetch round trip overlapped with the item)
# baseline (speedup 1.0000x reference)
; #define LAS __attribute__((address_space(3)))
; __device__ __forceinline__ void sscan_item(const Args& A, LAS unsigned char* lds, int tid, int lane, int wave, int bg, int h) {
;     const bf16_t* Z = (const bf16_t*)(A.ws + WS_Z); bf16_t* MIX = (bf16_t*)(A.ws + WS_XN);
;     LAS float* ZS = (LAS float*)(lds + SC_ZS); LAS float* OP = (LAS float*)(lds + SC_OP); LAS float* YB = (LAS float*)(lds + SC_Y); LAS float* CB = (LAS float*)(lds + SC_C);
;     const int fr = lane & 15, q4 = lane >> 4;
;     const int mt = wave & 1, nt = wave >> 1, cl = nt * 16 + fr, cg_ = h * 64 + cl;
;     bf16x8 bw[2], ba[2];
; #pragma unroll
;     for (int ks = 0; ks < 2; ++ks) { bw[ks] = *(const bf16x8*)((const bf16_t*)(A.ws + WS_W2T) + cg_ * 64 + ks * 32 + q4 * 8); ba[ks] = *(const bf16x8*)((const bf16_t*)(A.ws + WS_A2T) + cg_ * 64 + ks * 32 + q4 * 8); }
;     const float w0c = A.w0[cg_], a0c = A.a0[cg_], kkc = A.k_k[cg_], kac = A.k_a[cg_];
;     const float rkl = A.r_k[h * 64 + lane], lnw = A.ln_w[h * 64 + lane], lnb = A.ln_b[h * 64 + lane];
;     const int vr = (tid >> 3) & 31, kq = tid & 7;
; __global__ void __launch_bounds__(512, 2) hymba_fwd(Args A) {
;     ...
;         for (;;) {
.LBB0_316:
	v_readlane_b32 s14, v249, 3
	s_lshl_b32 s3, s14, 3
	s_and_b32 s3, s3, 0x1ffffff0
	v_or_b32_e32 v162, s3, v132
	s_lshl_b32 s3, s14, 4
	s_and_b32 s3, s3, 16
	v_mov_b32_e32 v77, 0
	v_or_b32_e32 v1, s3, v132
	v_lshlrev_b32_e32 v74, 1, v145
	v_mov_b32_e32 v75, v77
	v_mul_u32_u24_e32 v1, 0x500, v1
	v_lshlrev_b32_e32 v2, 2, v90
	s_lshl_b32 s8, s14, 2
	v_lshl_add_u64 v[78:79], s[68:69], 0, v[74:75]
	v_add3_u32 v75, 0, v1, v2
	v_or_b32_e32 v1, s3, v208
	s_movk_i32 s3, 0x140
	s_or_b32 s9, s8, 1
	v_mul_u32_u24_e32 v2, 0x140, v1
	v_mad_u32_u24 v1, v1, s3, v162
	s_mul_i32 s6, s9, 0x140
	v_lshl_add_u32 v85, v1, 2, 0
	v_lshlrev_b32_e32 v1, 2, v2
	v_lshlrev_b32_e32 v2, 2, v162
	s_mul_i32 s3, s14, 0x500
	s_lshl_b32 s7, s6, 2
	v_readlane_b32 s4, v249, 32
	v_add3_u32 v89, 0, v1, v2
	v_or_b32_e32 v1, s3, v145
	s_add_i32 s7, s7, 0
	v_add_u32_e32 v103, 2, v72
	v_lshlrev_b32_e32 v76, 1, v90
	v_readlane_b32 s5, v249, 33
	v_lshl_add_u32 v95, v1, 2, 0
	v_or_b32_e32 v1, s6, v145
	v_add_u32_e32 v98, s7, v137
	s_add_i32 s7, s6, 0x140
	v_lshlrev_b32_e32 v3, 3, v103
	v_lshl_add_u64 v[80:81], s[4:5], 0, v[76:77]
	v_readlane_b32 s4, v249, 34
	v_lshl_add_u32 v97, v1, 2, 0
	v_or_b32_e32 v1, s7, v145
	s_addk_i32 s6, 0x280
	v_or_b32_e32 v6, 1, v73
	v_or_b32_e32 v22, 1, v3
	v_readlane_b32 s5, v249, 35
	v_bfe_u32 v0, v144, 3, 5
	v_lshl_add_u32 v99, v1, 2, 0
	v_or_b32_e32 v1, s6, v145
	v_mul_u32_u24_e32 v7, 0x140, v6
	v_mul_u32_u24_e32 v23, 0x140, v22
	v_lshl_add_u64 v[82:83], s[4:5], 0, v[76:77]
	v_lshlrev_b32_e32 v84, 6, v0
	v_lshlrev_b32_e32 v76, 8, v0
	v_lshl_add_u32 v101, v1, 2, 0
	v_lshl_add_u32 v1, v207, 5, 0
	v_lshlrev_b32_e32 v0, 2, v0
	v_mul_u32_u24_e32 v4, 0xa00, v72
	v_lshlrev_b32_e32 v7, 2, v7
	v_mul_u32_u24_e32 v20, 0xa00, v103
	v_lshlrev_b32_e32 v23, 2, v23
	s_add_i32 s81, 0, 0x14000
	v_lshlrev_b32_e32 v4, 2, v4
	v_add_u32_e32 v109, v1, v7
	v_add3_u32 v110, 0, v7, v0
	v_add_u32_e32 v10, 0x500, v7
	v_add_u32_e32 v12, 0xa00, v7
	v_add_u32_e32 v14, 0xf00, v7
	v_add_u32_e32 v16, 0x1400, v7
	v_add_u32_e32 v18, 0x1900, v7
	v_add_u32_e32 v7, 0x1e00, v7
	v_lshlrev_b32_e32 v20, 2, v20
	v_add_u32_e32 v125, v1, v23
	v_add3_u32 v126, 0, v23, v0
	v_or_b32_e32 v25, 2, v3
	v_add_u32_e32 v26, 0x500, v23
	v_or_b32_e32 v27, 3, v3
	v_add_u32_e32 v28, 0xa00, v23
	v_or_b32_e32 v29, 4, v3
	v_add_u32_e32 v30, 0xf00, v23
	v_or_b32_e32 v31, 5, v3
	v_add_u32_e32 v32, 0x1400, v23
	v_or_b32_e32 v33, 6, v3
	v_add_u32_e32 v34, 0x1900, v23
	v_or_b32_e32 v3, 7, v3
	v_add_u32_e32 v23, 0x1e00, v23
	v_add_u32_e32 v2, s81, v0
	v_add_u32_e32 v107, v1, v4
	v_add3_u32 v108, 0, v4, v0
	v_lshlrev_b32_e32 v4, 7, v72
	v_add_u32_e32 v111, v1, v10
	v_add3_u32 v112, 0, v10, v0
	v_add_u32_e32 v113, v1, v12
	v_add3_u32 v114, 0, v12, v0
	v_add_u32_e32 v115, v1, v14
	v_add3_u32 v116, 0, v14, v0
	v_add_u32_e32 v117, v1, v16
	v_add3_u32 v118, 0, v16, v0
	v_add_u32_e32 v119, v1, v18
	v_add3_u32 v120, 0, v18, v0
	v_add_u32_e32 v121, v1, v7
	v_add3_u32 v122, 0, v7, v0
	v_add_u32_e32 v123, v1, v20
	v_add3_u32 v124, 0, v20, v0
	v_add_u32_e32 v127, v1, v26
	v_add3_u32 v135, 0, v26, v0
	v_add_u32_e32 v139, v1, v28
	v_add3_u32 v141, 0, v28, v0
	v_add_u32_e32 v143, v1, v30
	v_add3_u32 v147, 0, v30, v0
	v_add_u32_e32 v148, v1, v32
	v_add3_u32 v149, 0, v32, v0
	v_add_u32_e32 v150, v1, v34
	v_add3_u32 v151, 0, v34, v0
	v_add_u32_e32 v152, v1, v23
	v_add3_u32 v153, 0, v23, v0
	v_lshlrev_b32_e32 v0, 4, v3
	v_lshlrev_b32_e32 v1, 8, v3
	v_lshlrev_b32_e32 v8, 4, v6
	v_or_b32_e32 v9, 2, v73
	v_add_u32_e32 v3, 0, v4
	v_lshlrev_b32_e32 v10, 4, v9
	v_or_b32_e32 v11, 3, v73
	v_add_u32_e32 v156, 0x16000, v3
	v_add_u32_e32 v3, 0, v8
	s_lshl_b32 s3, s3, 2
	v_lshlrev_b32_e32 v12, 4, v11
	v_or_b32_e32 v13, 4, v73
	v_add_u32_e32 v158, 0x16000, v3
	v_add_u32_e32 v3, 0, v10
	s_add_i32 s3, s3, 0
	v_lshlrev_b32_e32 v14, 4, v13
	v_or_b32_e32 v15, 5, v73
	v_add_u32_e32 v160, 0x16000, v3
	v_add_u32_e32 v3, 0, v12
	v_add_u32_e32 v96, s3, v137
	v_readlane_b32 s3, v249, 0
	s_or_b32 s10, s8, 2
	s_lshl_b32 s7, s7, 2
	s_or_b32 s20, s8, 3
	s_lshl_b32 s6, s6, 2
	v_lshlrev_b32_e32 v16, 4, v15
	v_or_b32_e32 v17, 6, v73
	v_add_u32_e32 v163, 0x16000, v3
	v_add_u32_e32 v3, 0, v14
	s_andn2_b32 s3, s3, 63
	s_lshl_b32 s15, s9, 4
	s_add_i32 s7, s7, 0
	s_lshl_b32 s16, s10, 4
	s_add_i32 s6, s6, 0
	s_lshl_b32 s17, s20, 4
; #define LAS __attribute__((address_space(3)))
; __device__ __forceinline__ void sscan_item(const Args& A, LAS unsigned char* lds, int tid, int lane, int wave, int bg, int h) {
;     const bf16_t* Z = (const bf16_t*)(A.ws + WS_Z); bf16_t* MIX = (bf16_t*)(A.ws + WS_XN);
;     LAS float* ZS = (LAS float*)(lds + SC_ZS); LAS float* OP = (LAS float*)(lds + SC_OP); LAS float* YB = (LAS float*)(lds + SC_Y); LAS float* CB = (LAS float*)(lds + SC_C);
;     const int fr = lane & 15, q4 = lane >> 4;
;     const int mt = wave & 1, nt = wave >> 1, cl = nt * 16 + fr, cg_ = h * 64 + cl;
;     bf16x8 bw[2], ba[2];
; #pragma unroll
;     for (int ks = 0; ks < 2; ++ks) { bw[ks] = *(const bf16x8*)((const bf16_t*)(A.ws + WS_W2T) + cg_ * 64 + ks * 32 + q4 * 8); ba[ks] = *(const bf16x8*)((const bf16_t*)(A.ws + WS_A2T) + cg_ * 64 + ks * 32 + q4 * 8); }
;     const float w0c = A.w0[cg_], a0c = A.a0[cg_], kkc = A.k_k[cg_], kac = A.k_a[cg_];
;     const float rkl = A.r_k[h * 64 + lane], lnw = A.ln_w[h * 64 + lane], lnb = A.ln_b[h * 64 + lane];
;     const int vr = (tid >> 3) & 31, kq = tid & 7;
; __global__ void __launch_bounds__(512, 2) hymba_fwd(Args A) {
;     ...
;         for (;;) {
;             if (tid == 0) *s_item = (int)atomicAdd(ctl + CW_WORK + 2, 1u);
;             __syncthreads();
	v_lshlrev_b32_e32 v18, 4, v17
	v_or_b32_e32 v19, 7, v73
	v_add_u32_e32 v165, 0x16000, v3
	v_add_u32_e32 v3, 0, v16
	s_add_u32 s12, s86, 0x881a000
	v_lshlrev_b32_e32 v7, 4, v19
	v_add_u32_e32 v167, 0x16000, v3
	v_add_u32_e32 v3, 0, v18
	s_mov_b32 s11, 0
	v_readlane_b32 s40, v249, 14
	s_addc_u32 s13, s87, 0
	s_lshl_b32 s18, s14, 10
	v_lshlrev_b32_e32 v20, 7, v103
	v_add_u32_e32 v169, 0x16000, v3
	v_add_u32_e32 v3, 0, v7
	v_readlane_b32 s41, v249, 15
	v_readlane_b32 s42, v249, 16
	v_readlane_b32 s43, v249, 17
	v_readlane_b32 s44, v249, 18
	v_readlane_b32 s45, v249, 19
	v_readlane_b32 s46, v249, 20
	v_readlane_b32 s47, v249, 21
	v_readlane_b32 s48, v249, 22
	v_readlane_b32 s49, v249, 23
	v_readlane_b32 s50, v249, 24
	v_readlane_b32 s51, v249, 25
	v_readlane_b32 s52, v249, 26
	v_readlane_b32 s53, v249, 27
	v_readlane_b32 s54, v249, 28
	v_readlane_b32 s55, v249, 29
	v_writelane_b32 v249, s18, 38
	s_mulk_i32 s14, 0x1400
	s_and_b32 s18, s8, 4
	s_mov_b32 s19, s11
	s_mul_i32 s8, s9, 0x500
	v_lshlrev_b32_e32 v24, 4, v22
	v_add_u32_e32 v171, 0x16000, v3
	v_add_u32_e32 v3, 0, v20
	s_add_i32 s14, s14, 0
	v_writelane_b32 v249, s18, 40
	s_add_i32 s8, s8, 0
	v_lshlrev_b32_e32 v26, 4, v25
	v_add_u32_e32 v173, 0x16000, v3
	v_add_u32_e32 v3, 0, v24
	v_add_u32_e32 v105, s14, v137
	v_writelane_b32 v249, s19, 41
	s_lshl_b32 s14, s9, 8
	v_add_u32_e32 v106, s8, v137
	s_and_b32 s8, s9, 5
	s_mov_b32 s9, s11
	v_lshlrev_b32_e32 v28, 4, v27
	v_add_u32_e32 v175, 0x16000, v3
	v_add_u32_e32 v3, 0, v26
	v_writelane_b32 v249, s8, 42
	v_lshlrev_b32_e32 v30, 4, v29
	v_add_u32_e32 v177, 0x16000, v3
	v_add_u32_e32 v3, 0, v28
	v_writelane_b32 v249, s9, 43
	s_lshl_b32 s8, s10, 8
	v_lshlrev_b32_e32 v32, 4, v31
	v_add_u32_e32 v179, 0x16000, v3
	v_add_u32_e32 v3, 0, v30
	v_writelane_b32 v249, s8, 44
	s_and_b32 s8, s10, 6
	s_mov_b32 s9, s11
	v_lshlrev_b32_e32 v34, 4, v33
	v_add_u32_e32 v181, 0x16000, v3
	v_add_u32_e32 v3, 0, v32
	v_writelane_b32 v249, s8, 46
	v_lshlrev_b32_e32 v5, 11, v72
	v_lshlrev_b32_e32 v6, 8, v6
	v_lshlrev_b32_e32 v9, 8, v9
	v_lshlrev_b32_e32 v11, 8, v11
	v_lshlrev_b32_e32 v13, 8, v13
	v_lshlrev_b32_e32 v15, 8, v15
	v_lshlrev_b32_e32 v17, 8, v17
	v_lshlrev_b32_e32 v19, 8, v19
	v_lshlrev_b32_e32 v21, 11, v103
	v_lshlrev_b32_e32 v22, 8, v22
	v_lshlrev_b32_e32 v25, 8, v25
	v_lshlrev_b32_e32 v27, 8, v27
	v_lshlrev_b32_e32 v29, 8, v29
	v_lshlrev_b32_e32 v31, 8, v31
	v_lshlrev_b32_e32 v33, 8, v33
	v_add_u32_e32 v183, 0x16000, v3
	v_add_u32_e32 v3, 0, v34
	v_add_u32_e32 v0, 0, v0
	v_lshl_add_u64 v[86:87], s[44:45], 0, v[76:77]
	v_lshlrev_b32_e32 v88, 3, v207
	v_add_u32_e32 v94, 0x100, v85
	v_cmp_eq_u32_e64 s[4:5], 0, v145
	v_add_u32_e32 v100, s7, v137
	v_add_u32_e32 v102, s6, v137
	v_cmp_eq_u32_e64 s[6:7], 0, v207
	v_add_u32_e32 v104, s81, v137
	v_writelane_b32 v249, s9, 47
	s_lshl_b32 s8, s20, 8
	s_and_b32 s20, s20, 7
	s_mov_b32 s21, s11
	s_add_i32 s18, 0, 0x23ff0
	s_mov_b64 s[22:23], 0x2000
	s_movk_i32 s19, 0x2000
	s_movk_i32 s52, 0x1c00
	s_movk_i32 s53, 0x1a00
	s_mov_b32 s54, 0x3f200000
	s_mov_b32 s55, 0x3fb8aa3b
	s_mov_b32 s56, 0xc2ce8ed0
	s_mov_b32 s57, 0x42b17218
	v_mov_b32_e32 v154, 0x3ca908c9
	s_brev_b32 s58, -2
	s_mov_b32 s59, 0xf800000
	v_mov_b32_e32 v155, 0x260
	v_add_u32_e32 v157, v2, v5
	v_add_u32_e32 v159, v2, v6
	v_add_u32_e32 v161, v2, v9
	v_add_u32_e32 v164, v2, v11
	v_add_u32_e32 v166, v2, v13
	v_add_u32_e32 v168, v2, v15
	v_add_u32_e32 v170, v2, v17
	v_add_u32_e32 v172, v2, v19
	v_add_u32_e32 v174, v2, v21
	v_add_u32_e32 v176, v2, v22
	v_add_u32_e32 v178, v2, v25
	v_add_u32_e32 v180, v2, v27
	v_add_u32_e32 v182, v2, v29
	v_add_u32_e32 v184, v2, v31
	v_add_u32_e32 v185, 0x16000, v3
	v_add_u32_e32 v186, v2, v33
	v_add_u32_e32 v187, 0x16000, v0
	v_add_u32_e32 v188, v2, v1
	v_mov_b32_e32 v189, 0x3a27c5ac
	v_mov_b32_e32 v190, 0x640
	v_mov_b32_e32 v191, 0x600
	v_mov_b32_e32 v192, 0x7f800000
	v_writelane_b32 v249, s8, 48
	s_and_saveexec_b64 s[98:99], s[0:1]
	s_cbranch_execz .Lfpf_ss
	s_waitcnt vmcnt(0)
	s_mov_b64 s[100:101], exec
	v_mbcnt_lo_u32_b32 v246, s100, 0
	v_mbcnt_hi_u32_b32 v246, s101, v246
	v_cmp_eq_u32_e32 vcc, 0, v246
	s_and_b64 exec, exec, vcc
	s_bcnt1_i32_b64 s100, s[100:101]
	v_mov_b32_e32 v246, s100
	s_nop 0
	global_atomic_add v246, v77, v246, s[96:97] offset:8 sc0
.Lfpf_ss:
	s_or_b64 exec, exec, s[98:99]
	s_branch .LBB0_320

; __global__ void __launch_bounds__(512, 2) hymba_fwd(Args A) {
;     ...
;         for (;;) {
;             if (tid == 0) *s_item = (int)atomicAdd(ctl + CW_WORK + 2, 1u);
;             __syncthreads();
;             const int r = *s_item;
;             __syncthreads();
;             if (r >= 256) break;
.LBB0_320:
	s_and_saveexec_b64 s[8:9], s[0:1]
	s_cbranch_execz .LBB0_324
	s_mov_b64 s[26:27], exec
	v_mbcnt_lo_u32_b32 v0, s26, 0
	v_mbcnt_hi_u32_b32 v0, s27, v0
	v_cmp_eq_u32_e32 vcc, 0, v0
	s_and_saveexec_b64 s[24:25], vcc
	s_cbranch_execz .LBB0_323
	s_bcnt1_i32_b64 s10, s[26:27]
	s_waitcnt vmcnt(0)
	v_mov_b32_e32 v1, v246
	v_mov_b32_e32 v246, s10
	s_nop 0
	global_atomic_add v246, v77, v246, s[96:97] offset:8 sc0
.LBB0_323:
	s_or_b64 exec, exec, s[24:25]
	s_nop 0
	v_readfirstlane_b32 s10, v1
	v_mov_b32_e32 v1, s18
	s_nop 0
	v_add_u32_e32 v0, s10, v0
	ds_write_b32 v1, v0

; #define LAS __attribute__((address_space(3)))
; __device__ __forceinline__ void attn_sample_item(const Args& A, LAS unsigned char* lds, int tid, int lane, int wave, int b, int kvh) {
;     const bf16_t* Z = (const bf16_t*)(A.ws + WS_Z); bf16_t* MIX = (bf16_t*)(A.ws + WS_XN);
;     const float* ct = (const float*)(A.ws + WS_ROPE); const float* st = ct + 2056 * 8;
;     LAS float* SK = (LAS float*)(lds + SA_K); LAS float* SV = (LAS float*)(lds + SA_V); LAS float* SQ = (LAS float*)(lds + SA_Q); LAS float* SP = (LAS float*)(lds + SA_P);
;     float* ko = A.out + OUT_KS + (size_t)b * 128 * 128; float* vo = A.out + OUT_VS + (size_t)b * 128 * 128;
;     const int tn_ = tid >> 6, dn_ = tid & 63; const size_t rown_ = (size_t)MP + b * 8 + tn_; const bf16_t* kpn_ = Z + rown_ * NZ + O_K + kvh * 64;
;     const unsigned short kraw_ = kpn_[dn_], kpar_ = kpn_[dn_ ^ 8], vraw_ = Z[rown_ * NZ + O_V + kvh * 64 + dn_];
;     const float kc_ = ct[(2048 + tn_) * 8 + (dn_ & 7)], ks_ = st[(2048 + tn_) * 8 + (dn_ & 7)];
;     unsigned short qraw_[4], qpar_[4]; float qc_[4], qs_[4];
; #pragma unroll
;     for (int i = 0; i < 4; ++i) { const int idx = tid + 512 * i, qi = idx >> 6, d = idx & 63, t = qi >> 2, g = qi & 3, hq = kvh * 4 + g; const bf16_t* qp = Z + ((size_t)MP + b * 8 + t) * NZ + O_Q + hq * 64;
;         qraw_[i] = qp[d]; qpar_[i] = qp[d ^ 8]; qc_[i] = ct[(2048 + t) * 8 + (d & 7)]; qs_[i] = st[(2048 + t) * 8 + (d & 7)]; }
;     u32x2 graw_; { const int qi = tid >> 4, d0 = (tid & 15) * 4, t = qi >> 2, g = qi & 3, hq = kvh * 4 + g; graw_ = *(const u32x2*)(Z + ((size_t)MP + b * 8 + t) * NZ + O_GA + hq * 64 + d0); }
; __global__ void __launch_bounds__(512, 2) hymba_fwd(Args A) {
;     ...
;         for (;;) {
;             if (tid == 0) *s_item = (int)atomicAdd(ctl + CW_WORK + 4, 1u);
.LBB0_432:
	v_lshrrev_b32_e32 v32, 6, v144
	s_add_u32 s3, s86, 0xa0ea000
	v_lshlrev_b32_e32 v2, 2, v207
	v_lshlrev_b32_e32 v3, 5, v32
	s_mov_b32 s4, 0x10000
	s_addc_u32 s22, s87, 0
	v_or3_b32 v34, v3, v2, s4
	v_or_b32_e32 v3, 0x4000, v207
	v_mov_b32_e32 v35, 0
	v_or_b32_e32 v4, v73, v3
	s_add_u32 s23, s86, 0x98ea000
	v_lshl_add_u64 v[36:37], s[88:89], 0, v[34:35]
	v_lshl_add_u64 v[38:39], s[90:91], 0, v[34:35]
	v_lshlrev_b32_e32 v34, 2, v4
	v_add_u32_e32 v4, 0x200, v144
	s_addc_u32 s24, s87, 0
	v_mov_b32_e32 v16, 0xf0
	s_add_i32 s10, 0, 0x11b00
	v_lshrrev_b32_e32 v44, 8, v4
	v_lshrrev_b32_e32 v51, 4, v4
	v_lshl_add_u32 v84, v32, 1, v16
	v_add_u32_e32 v16, s10, v137
	v_and_b32_e32 v4, 0x7c0, v4
	s_movk_i32 s10, 0x7c0
	v_lshl_add_u32 v86, v4, 2, v16
	v_mov_b32_e32 v4, 0x400
	v_lshlrev_b32_e32 v3, 2, v3
	v_or_b32_e32 v5, 0x400, v144
	v_bitop3_b32 v4, v144, s10, v4 bitop3:0xc8
	v_readlane_b32 s10, v249, 3
	v_lshl_add_u64 v[40:41], s[88:89], 0, v[34:35]
	v_lshl_add_u64 v[42:43], s[90:91], 0, v[34:35]
	v_lshl_or_b32 v34, v44, 5, v3
	v_lshrrev_b32_e32 v50, 8, v5
	v_add_u32_e32 v6, 0x600, v144
	s_mulk_i32 s10, 0x880
	v_lshl_add_u64 v[46:47], s[88:89], 0, v[34:35]
	v_lshl_add_u64 v[48:49], s[90:91], 0, v[34:35]
	v_lshl_or_b32 v34, v50, 5, v3
	v_lshrrev_b32_e32 v56, 8, v6
	v_lshrrev_b32_e32 v45, 4, v144
	v_and_b32_e32 v62, 60, v146
	v_lshrrev_b32_e32 v63, 4, v5
	v_lshrrev_b32_e32 v73, 4, v6
	v_mov_b32_e32 v8, 0xfffffc00
	v_or_b32_e32 v14, 0x80, v32
	v_lshl_add_u32 v87, v4, 2, v16
	v_and_b32_e32 v4, 0xfc0, v6
	s_add_i32 s10, s10, 0
	v_add_u32_e32 v1, 0, v137
	v_xor_b32_e32 v0, 8, v145
	v_and_b32_e32 v2, 0xc0, v144
	v_lshl_add_u64 v[52:53], s[88:89], 0, v[34:35]
	v_lshl_add_u64 v[54:55], s[90:91], 0, v[34:35]
	v_lshl_or_b32 v34, v56, 5, v3
	v_lshl_add_u32 v3, v62, 2, 0
	v_mul_u32_u24_e32 v5, 0x104, v45
	v_mul_u32_u24_e32 v7, 0x110, v45
	s_movk_i32 s4, 0x7f
	v_lshl_add_u32 v80, v45, 7, v8
	v_mul_u32_u24_e32 v8, 0x104, v51
	v_mul_u32_u24_e32 v9, 0x110, v51
	v_mul_u32_u24_e32 v10, 0x104, v63
	v_mul_u32_u24_e32 v11, 0x110, v63
	v_mul_u32_u24_e32 v12, 0x104, v73
	v_mul_u32_u24_e32 v13, 0x110, v73
	v_mul_u32_u24_e32 v15, 0x104, v14
	v_mul_u32_u24_e32 v14, 0x110, v14
	v_and_b32_e32 v17, 0x3c0, v144
	v_lshl_add_u32 v88, v4, 2, v16
	s_add_i32 s10, s10, 0x13b00
	v_mov_b32_e32 v4, 0x8a80
	s_mov_b32 s11, 0
	v_mov_b32_e32 v33, v35
	v_mov_b32_e32 v57, v35
	v_lshl_add_u64 v[58:59], s[88:89], 0, v[34:35]
	v_lshl_add_u64 v[60:61], s[90:91], 0, v[34:35]
	v_bfe_u32 v163, v144, 4, 2
	s_movk_i32 s25, 0x104
	v_cmp_lt_u32_e64 s[4:5], s4, v144
	v_lshlrev_b32_e32 v81, 7, v51
	v_lshlrev_b32_e32 v82, 7, v63
	v_lshlrev_b32_e32 v83, 7, v73
	v_cmp_gt_u32_e64 s[6:7], 8, v145
	v_cmp_lt_u32_e64 s[8:9], 7, v145
	s_movk_i32 s26, 0x80
	v_lshl_add_u32 v85, v17, 2, v16
	v_add_u32_e32 v89, s10, v137
	v_mul_u32_u24_e32 v90, 0x220, v45
	v_lshl_add_u32 v91, v132, 4, v4
	s_add_i32 s27, 0, 0x23ff0
	s_movk_i32 s28, 0xff
	s_movk_i32 s29, 0x1c00
	s_mov_b64 s[12:13], 0x1500
	v_lshlrev_b32_e32 v64, 1, v0
	s_movk_i32 s34, 0x1000
	v_lshlrev_b32_e32 v92, 1, v2
	s_mov_b64 s[14:15], 0x1100
	v_add_u32_e32 v93, v3, v5
	v_add_u32_e32 v94, v3, v7
	v_add_u32_e32 v95, v3, v8
	v_add_u32_e32 v96, v3, v9
	v_add_u32_e32 v97, v3, v10
	v_add_u32_e32 v98, v3, v11
	v_add_u32_e32 v99, v3, v12
	v_add_u32_e32 v100, v3, v13
	v_add_u32_e32 v101, v1, v15
	v_add_u32_e32 v102, v1, v14
	s_mov_b32 s35, 0xf0f1
	s_add_i32 s36, 0, 0x11b30
	s_movk_i32 s37, 0xeff
	v_mov_b32_e32 v103, 0x1c00
	v_mov_b32_e32 v104, 0xf149f2ca
	v_readlane_b32 s73, v249, 50
	s_and_saveexec_b64 s[98:99], s[0:1]
	s_cbranch_execz .Lfpf_sa
	s_waitcnt vmcnt(0)
	s_mov_b64 s[100:101], exec
	v_mbcnt_lo_u32_b32 v246, s100, 0
	v_mbcnt_hi_u32_b32 v246, s101, v246
	v_cmp_eq_u32_e32 vcc, 0, v246
	s_and_b64 exec, exec, vcc
	s_bcnt1_i32_b64 s100, s[100:101]
	v_mov_b32_e32 v246, s100
	s_nop 0
	global_atomic_add v246, v35, v246, s[96:97] offset:16 sc0

; __global__ void __launch_bounds__(512, 2) hymba_fwd(Args A) {
;     ...
;         for (;;) {
;             if (tid == 0) *s_item = (int)atomicAdd(ctl + CW_WORK + 4, 1u);
;             __syncthreads();
;             const int r = *s_item;
;             __syncthreads();
;             if (r >= N_SA) break;
.LBB0_434:
	s_and_saveexec_b64 s[16:17], s[0:1]
	s_cbranch_execz .LBB0_438
	s_mov_b64 s[20:21], exec
	v_mbcnt_lo_u32_b32 v0, s20, 0
	v_mbcnt_hi_u32_b32 v0, s21, v0
	v_cmp_eq_u32_e32 vcc, 0, v0
	s_and_saveexec_b64 s[18:19], vcc
	s_cbranch_execz .LBB0_437
	s_bcnt1_i32_b64 s10, s[20:21]
	s_waitcnt vmcnt(0)
	v_mov_b32_e32 v1, v246
	v_mov_b32_e32 v246, s10
	s_nop 0
	global_atomic_add v246, v35, v246, s[96:97] offset:16 sc0
.LBB0_437:
	s_or_b64 exec, exec, s[18:19]
	s_nop 0
	v_readfirstlane_b32 s10, v1
	v_mov_b32_e32 v1, s27
	s_nop 0
	v_add_u32_e32 v0, s10, v0
	ds_write_b32 v1, v0
